# Hyena context-token filter taps (layer 0): the 128 weight loads per tap pair batched 32 at a time instead of two per wait
# speedup vs baseline: 1.0164x; 1.0125x over previous
; DI void hyena_unit(KP p, int l, int c, char* smem) {
;     ...
;     for (int o = 0; o < 2; ++o) {
;       const int colf = o * 512 + c, colb = 1024 + o * 512 + c;
;       const float skip = p->hy_skip[(l * 2 + o) * 512 + c];
;       const int gcol = (o == 0 ? 512 : 1024) + c;
;       const float gw0 = cw[gcol], gw1 = cw[1536 + gcol], gw2 = cw[3072 + gcol], gb = cb[gcol];
;       const float vw0 = cw[c], vw1 = cw[1536 + c], vw2 = cw[3072 + c], vb = cb[c];
;       __syncthreads();
;       {
;         float hf = 0.f, hb = 0.f;
;         const f32x4* hr = (const f32x4*)(hid2 + t * 64);
; #pragma unroll
;         for (int j4 = 0; j4 < 16; ++j4) {
;           const f32x4 hv = hr[j4];
;           const float* wf = wout + (size_t)(4 * j4) * 2048;
;           hf += hv.x * wf[colf] + hv.y * wf[2048 + colf] + hv.z * wf[4096 + colf] + hv.w * wf[6144 + colf];
;           hb += hv.x * wf[colb] + hv.y * wf[2048 + colb] + hv.z * wf[4096 + colb] + hv.w * wf[6144 + colb];
.LBB0_1029:
	s_add_i32 s24, s22, s86
	s_ashr_i32 s25, s24, 31
	s_add_i32 s22, s22, s6
	s_lshl_b64 s[24:25], s[24:25], 2
	s_add_u32 s26, s18, s24
	s_addc_u32 s27, s19, s25
	global_load_dword v53, v199, s[26:27]
	s_and_b64 s[26:27], s[16:17], exec
	s_cselect_b32 s7, 0x200, s62
	s_lshl_b32 s23, s7, 2
	s_add_u32 s26, s88, s23
	s_addc_u32 s27, s89, 0
	v_mov_b32_e32 v6, s23
	s_ashr_i32 s23, s22, 31
	global_load_dword v47, v6, s[88:89]
	global_load_dword v49, v235, s[26:27] offset:2048
	global_load_dword v48, v229, s[26:27]
	global_load_dword v50, v6, s[94:95]
	global_load_dword v40, v199, s[88:89]
	global_load_dword v51, v199, s[90:91]
	global_load_dword v41, v199, s[92:93]
	global_load_dword v52, v199, s[94:95]
	s_add_u32 s26, s21, s24
	s_addc_u32 s27, s28, s25
	s_barrier
	global_load_dwordx4 v[68:71], v[14:15], off
	global_load_dwordx4 v[72:75], v[14:15], off offset:16
	global_load_dwordx4 v[76:79], v[14:15], off offset:32
	global_load_dwordx4 v[80:83], v[14:15], off offset:48
	global_load_dwordx4 v[84:87], v[14:15], off offset:64
	global_load_dwordx4 v[88:91], v[14:15], off offset:80
	global_load_dwordx4 v[92:95], v[14:15], off offset:96
	global_load_dwordx4 v[96:99], v[14:15], off offset:112
	global_load_dwordx4 v[100:103], v[14:15], off offset:128
	global_load_dwordx4 v[104:107], v[14:15], off offset:144
	global_load_dwordx4 v[108:111], v[14:15], off offset:160
	global_load_dwordx4 v[112:115], v[14:15], off offset:176
	global_load_dwordx4 v[116:119], v[14:15], off offset:192
	global_load_dwordx4 v[120:123], v[14:15], off offset:208
	global_load_dwordx4 v[124:127], v[14:15], off offset:224
	global_load_dwordx4 v[128:131], v[14:15], off offset:240
	s_lshl_b64 s[22:23], s[22:23], 2
	s_add_u32 s22, s21, s22
	s_addc_u32 s23, s28, s23
	v_mov_b32_e32 v11, 0
	v_mov_b32_e32 v7, 0
	global_load_dword v132, v199, s[26:27]
	global_load_dword v133, v1, s[26:27]
	global_load_dword v134, v215, s[26:27]
	global_load_dword v135, v217, s[26:27]
	global_load_dword v136, v199, s[22:23]
	global_load_dword v137, v1, s[22:23]
	global_load_dword v138, v215, s[22:23]
	global_load_dword v139, v217, s[22:23]
	s_add_u32 s26, s26, 0x8000
	s_addc_u32 s27, s27, 0
	s_add_u32 s22, s22, 0x8000
	s_addc_u32 s23, s23, 0
	global_load_dword v140, v199, s[26:27]
	global_load_dword v141, v1, s[26:27]
	global_load_dword v142, v215, s[26:27]
	global_load_dword v143, v217, s[26:27]
	global_load_dword v144, v199, s[22:23]
	global_load_dword v145, v1, s[22:23]
	global_load_dword v146, v215, s[22:23]
	global_load_dword v147, v217, s[22:23]
	s_add_u32 s26, s26, 0x8000
	s_addc_u32 s27, s27, 0
	s_add_u32 s22, s22, 0x8000
	s_addc_u32 s23, s23, 0
	global_load_dword v148, v199, s[26:27]
	global_load_dword v149, v1, s[26:27]
	global_load_dword v150, v215, s[26:27]
	global_load_dword v151, v217, s[26:27]
	global_load_dword v152, v199, s[22:23]
	global_load_dword v153, v1, s[22:23]
	global_load_dword v154, v215, s[22:23]
	global_load_dword v155, v217, s[22:23]
	s_add_u32 s26, s26, 0x8000
	s_addc_u32 s27, s27, 0
	s_add_u32 s22, s22, 0x8000
	s_addc_u32 s23, s23, 0
	global_load_dword v156, v199, s[26:27]
	global_load_dword v157, v1, s[26:27]
	global_load_dword v158, v215, s[26:27]
	global_load_dword v159, v217, s[26:27]
	global_load_dword v160, v199, s[22:23]
	global_load_dword v161, v1, s[22:23]
	global_load_dword v162, v215, s[22:23]
	global_load_dword v163, v217, s[22:23]
	s_add_u32 s26, s26, 0x8000
	s_addc_u32 s27, s27, 0
	s_add_u32 s22, s22, 0x8000
	s_addc_u32 s23, s23, 0
	global_load_dword v164, v199, s[26:27]
	global_load_dword v165, v1, s[26:27]
	global_load_dword v166, v215, s[26:27]
	global_load_dword v167, v217, s[26:27]
	global_load_dword v168, v199, s[22:23]
	global_load_dword v169, v1, s[22:23]
	global_load_dword v170, v215, s[22:23]
	global_load_dword v171, v217, s[22:23]
	s_add_u32 s26, s26, 0x8000
	s_addc_u32 s27, s27, 0
	s_add_u32 s22, s22, 0x8000
	s_addc_u32 s23, s23, 0
	global_load_dword v172, v199, s[26:27]
	global_load_dword v173, v1, s[26:27]
	global_load_dword v174, v215, s[26:27]
	global_load_dword v175, v217, s[26:27]
	global_load_dword v176, v199, s[22:23]
	global_load_dword v177, v1, s[22:23]
	global_load_dword v178, v215, s[22:23]
	global_load_dword v179, v217, s[22:23]
	s_add_u32 s26, s26, 0x8000
	s_addc_u32 s27, s27, 0
	s_add_u32 s22, s22, 0x8000
	s_addc_u32 s23, s23, 0
	global_load_dword v180, v199, s[26:27]
	global_load_dword v181, v1, s[26:27]
	global_load_dword v182, v215, s[26:27]
	global_load_dword v183, v217, s[26:27]
	global_load_dword v184, v199, s[22:23]
	global_load_dword v185, v1, s[22:23]
	global_load_dword v186, v215, s[22:23]
	global_load_dword v187, v217, s[22:23]
	s_add_u32 s26, s26, 0x8000
	s_addc_u32 s27, s27, 0
	s_add_u32 s22, s22, 0x8000
	s_addc_u32 s23, s23, 0
	global_load_dword v188, v199, s[26:27]
	global_load_dword v189, v1, s[26:27]
	global_load_dword v190, v215, s[26:27]
	global_load_dword v191, v217, s[26:27]
	global_load_dword v192, v199, s[22:23]
	global_load_dword v193, v1, s[22:23]
	global_load_dword v194, v215, s[22:23]
	global_load_dword v195, v217, s[22:23]
	s_add_u32 s26, s26, 0x8000
	s_addc_u32 s27, s27, 0
	s_add_u32 s22, s22, 0x8000
	s_addc_u32 s23, s23, 0
	s_waitcnt vmcnt(32)
; DI void hyena_unit(KP p, int l, int c, char* smem) {
;     ...
; #pragma unroll
;         for (int j4 = 0; j4 < 16; ++j4) {
;           const f32x4 hv = hr[j4];
;           const float* wf = wout + (size_t)(4 * j4) * 2048;
;           hf += hv.x * wf[colf] + hv.y * wf[2048 + colf] + hv.z * wf[4096 + colf] + hv.w * wf[6144 + colf];
;           hb += hv.x * wf[colb] + hv.y * wf[2048 + colb] + hv.z * wf[4096 + colb] + hv.w * wf[6144 + colb];
	v_fmac_f32_e32 v11, v68, v132
	v_fmac_f32_e32 v7, v68, v136
	v_fmac_f32_e32 v11, v69, v133
	v_fmac_f32_e32 v7, v69, v137
	v_fmac_f32_e32 v11, v70, v134
	v_fmac_f32_e32 v7, v70, v138
	v_fmac_f32_e32 v11, v71, v135
	v_fmac_f32_e32 v7, v71, v139
	v_fmac_f32_e32 v11, v72, v140
	v_fmac_f32_e32 v7, v72, v144
	v_fmac_f32_e32 v11, v73, v141
	v_fmac_f32_e32 v7, v73, v145
	v_fmac_f32_e32 v11, v74, v142
	v_fmac_f32_e32 v7, v74, v146
	v_fmac_f32_e32 v11, v75, v143
	v_fmac_f32_e32 v7, v75, v147
	v_fmac_f32_e32 v11, v76, v148
	v_fmac_f32_e32 v7, v76, v152
	v_fmac_f32_e32 v11, v77, v149
	v_fmac_f32_e32 v7, v77, v153
	v_fmac_f32_e32 v11, v78, v150
	v_fmac_f32_e32 v7, v78, v154
	v_fmac_f32_e32 v11, v79, v151
	v_fmac_f32_e32 v7, v79, v155
	v_fmac_f32_e32 v11, v80, v156
	v_fmac_f32_e32 v7, v80, v160
	v_fmac_f32_e32 v11, v81, v157
	v_fmac_f32_e32 v7, v81, v161
	v_fmac_f32_e32 v11, v82, v158
	v_fmac_f32_e32 v7, v82, v162
	v_fmac_f32_e32 v11, v83, v159
	v_fmac_f32_e32 v7, v83, v163
	global_load_dword v132, v199, s[26:27]
	global_load_dword v133, v1, s[26:27]
	global_load_dword v134, v215, s[26:27]
	global_load_dword v135, v217, s[26:27]
	global_load_dword v136, v199, s[22:23]
	global_load_dword v137, v1, s[22:23]
	global_load_dword v138, v215, s[22:23]
	global_load_dword v139, v217, s[22:23]
	s_add_u32 s26, s26, 0x8000
	s_addc_u32 s27, s27, 0
	s_add_u32 s22, s22, 0x8000
	s_addc_u32 s23, s23, 0
	global_load_dword v140, v199, s[26:27]
	global_load_dword v141, v1, s[26:27]
	global_load_dword v142, v215, s[26:27]
	global_load_dword v143, v217, s[26:27]
	global_load_dword v144, v199, s[22:23]
	global_load_dword v145, v1, s[22:23]
	global_load_dword v146, v215, s[22:23]
	global_load_dword v147, v217, s[22:23]
	s_add_u32 s26, s26, 0x8000
	s_addc_u32 s27, s27, 0
	s_add_u32 s22, s22, 0x8000
	s_addc_u32 s23, s23, 0
	global_load_dword v148, v199, s[26:27]
	global_load_dword v149, v1, s[26:27]
	global_load_dword v150, v215, s[26:27]
	global_load_dword v151, v217, s[26:27]
	global_load_dword v152, v199, s[22:23]
	global_load_dword v153, v1, s[22:23]
	global_load_dword v154, v215, s[22:23]
	global_load_dword v155, v217, s[22:23]
	s_add_u32 s26, s26, 0x8000
	s_addc_u32 s27, s27, 0
	s_add_u32 s22, s22, 0x8000
	s_addc_u32 s23, s23, 0
	global_load_dword v156, v199, s[26:27]
	global_load_dword v157, v1, s[26:27]
	global_load_dword v158, v215, s[26:27]
	global_load_dword v159, v217, s[26:27]
	global_load_dword v160, v199, s[22:23]
	global_load_dword v161, v1, s[22:23]
	global_load_dword v162, v215, s[22:23]
	global_load_dword v163, v217, s[22:23]
	s_add_u32 s26, s26, 0x8000
	s_addc_u32 s27, s27, 0
	s_add_u32 s22, s22, 0x8000
	s_addc_u32 s23, s23, 0
	s_waitcnt vmcnt(32)
; DI void hyena_unit(KP p, int l, int c, char* smem) {
;     ...
; #pragma unroll
;         for (int j4 = 0; j4 < 16; ++j4) {
;           const f32x4 hv = hr[j4];
;           const float* wf = wout + (size_t)(4 * j4) * 2048;
;           hf += hv.x * wf[colf] + hv.y * wf[2048 + colf] + hv.z * wf[4096 + colf] + hv.w * wf[6144 + colf];
;           hb += hv.x * wf[colb] + hv.y * wf[2048 + colb] + hv.z * wf[4096 + colb] + hv.w * wf[6144 + colb];
;         }
;         const float dec = expf(-((float)t / 255.f) * delta);
;         hf *= dec; hb *= dec;
;         if (t == 0) kk[255] = hf + hb + skip;
;         else { kk[255 + t] = hf; kk[255 - t] = hb; }
	v_fmac_f32_e32 v11, v84, v164
	v_fmac_f32_e32 v7, v84, v168
	v_fmac_f32_e32 v11, v85, v165
	v_fmac_f32_e32 v7, v85, v169
	v_fmac_f32_e32 v11, v86, v166
	v_fmac_f32_e32 v7, v86, v170
	v_fmac_f32_e32 v11, v87, v167
	v_fmac_f32_e32 v7, v87, v171
	v_fmac_f32_e32 v11, v88, v172
	v_fmac_f32_e32 v7, v88, v176
	v_fmac_f32_e32 v11, v89, v173
	v_fmac_f32_e32 v7, v89, v177
	v_fmac_f32_e32 v11, v90, v174
	v_fmac_f32_e32 v7, v90, v178
	v_fmac_f32_e32 v11, v91, v175
	v_fmac_f32_e32 v7, v91, v179
	v_fmac_f32_e32 v11, v92, v180
	v_fmac_f32_e32 v7, v92, v184
	v_fmac_f32_e32 v11, v93, v181
	v_fmac_f32_e32 v7, v93, v185
	v_fmac_f32_e32 v11, v94, v182
	v_fmac_f32_e32 v7, v94, v186
	v_fmac_f32_e32 v11, v95, v183
	v_fmac_f32_e32 v7, v95, v187
	v_fmac_f32_e32 v11, v96, v188
	v_fmac_f32_e32 v7, v96, v192
	v_fmac_f32_e32 v11, v97, v189
	v_fmac_f32_e32 v7, v97, v193
	v_fmac_f32_e32 v11, v98, v190
	v_fmac_f32_e32 v7, v98, v194
	v_fmac_f32_e32 v11, v99, v191
	v_fmac_f32_e32 v7, v99, v195
	global_load_dword v164, v199, s[26:27]
	global_load_dword v165, v1, s[26:27]
	global_load_dword v166, v215, s[26:27]
	global_load_dword v167, v217, s[26:27]
	global_load_dword v168, v199, s[22:23]
	global_load_dword v169, v1, s[22:23]
	global_load_dword v170, v215, s[22:23]
	global_load_dword v171, v217, s[22:23]
	s_add_u32 s26, s26, 0x8000
	s_addc_u32 s27, s27, 0
	s_add_u32 s22, s22, 0x8000
	s_addc_u32 s23, s23, 0
	global_load_dword v172, v199, s[26:27]
	global_load_dword v173, v1, s[26:27]
	global_load_dword v174, v215, s[26:27]
	global_load_dword v175, v217, s[26:27]
	global_load_dword v176, v199, s[22:23]
	global_load_dword v177, v1, s[22:23]
	global_load_dword v178, v215, s[22:23]
	global_load_dword v179, v217, s[22:23]
	s_add_u32 s26, s26, 0x8000
	s_addc_u32 s27, s27, 0
	s_add_u32 s22, s22, 0x8000
	s_addc_u32 s23, s23, 0
	global_load_dword v180, v199, s[26:27]
	global_load_dword v181, v1, s[26:27]
	global_load_dword v182, v215, s[26:27]
	global_load_dword v183, v217, s[26:27]
	global_load_dword v184, v199, s[22:23]
	global_load_dword v185, v1, s[22:23]
	global_load_dword v186, v215, s[22:23]
	global_load_dword v187, v217, s[22:23]
	s_add_u32 s26, s26, 0x8000
	s_addc_u32 s27, s27, 0
	s_add_u32 s22, s22, 0x8000
	s_addc_u32 s23, s23, 0
	global_load_dword v188, v199, s[26:27]
	global_load_dword v189, v1, s[26:27]
	global_load_dword v190, v215, s[26:27]
	global_load_dword v191, v217, s[26:27]
	global_load_dword v192, v199, s[22:23]
	global_load_dword v193, v1, s[22:23]
	global_load_dword v194, v215, s[22:23]
	global_load_dword v195, v217, s[22:23]
	s_add_u32 s26, s26, 0x8000
	s_addc_u32 s27, s27, 0
	s_add_u32 s22, s22, 0x8000
	s_addc_u32 s23, s23, 0
	s_waitcnt vmcnt(32)
	v_fmac_f32_e32 v11, v100, v132
	v_fmac_f32_e32 v7, v100, v136
	v_fmac_f32_e32 v11, v101, v133
	v_fmac_f32_e32 v7, v101, v137
	v_fmac_f32_e32 v11, v102, v134
	v_fmac_f32_e32 v7, v102, v138
	v_fmac_f32_e32 v11, v103, v135
	v_fmac_f32_e32 v7, v103, v139
	v_fmac_f32_e32 v11, v104, v140
	v_fmac_f32_e32 v7, v104, v144
	v_fmac_f32_e32 v11, v105, v141
	v_fmac_f32_e32 v7, v105, v145
	v_fmac_f32_e32 v11, v106, v142
	v_fmac_f32_e32 v7, v106, v146
	v_fmac_f32_e32 v11, v107, v143
	v_fmac_f32_e32 v7, v107, v147
	v_fmac_f32_e32 v11, v108, v148
	v_fmac_f32_e32 v7, v108, v152
	v_fmac_f32_e32 v11, v109, v149
	v_fmac_f32_e32 v7, v109, v153
	v_fmac_f32_e32 v11, v110, v150
	v_fmac_f32_e32 v7, v110, v154
	v_fmac_f32_e32 v11, v111, v151
	v_fmac_f32_e32 v7, v111, v155
	v_fmac_f32_e32 v11, v112, v156
	v_fmac_f32_e32 v7, v112, v160
	v_fmac_f32_e32 v11, v113, v157
	v_fmac_f32_e32 v7, v113, v161
	v_fmac_f32_e32 v11, v114, v158
	v_fmac_f32_e32 v7, v114, v162
	v_fmac_f32_e32 v11, v115, v159
	v_fmac_f32_e32 v7, v115, v163
	s_waitcnt vmcnt(0)
	v_fmac_f32_e32 v11, v116, v164
	v_fmac_f32_e32 v7, v116, v168
	v_fmac_f32_e32 v11, v117, v165
	v_fmac_f32_e32 v7, v117, v169
	v_fmac_f32_e32 v11, v118, v166
	v_fmac_f32_e32 v7, v118, v170
	v_fmac_f32_e32 v11, v119, v167
	v_fmac_f32_e32 v7, v119, v171
	v_fmac_f32_e32 v11, v120, v172
	v_fmac_f32_e32 v7, v120, v176
	v_fmac_f32_e32 v11, v121, v173
	v_fmac_f32_e32 v7, v121, v177
	v_fmac_f32_e32 v11, v122, v174
	v_fmac_f32_e32 v7, v122, v178
	v_fmac_f32_e32 v11, v123, v175
	v_fmac_f32_e32 v7, v123, v179
	v_fmac_f32_e32 v11, v124, v180
	v_fmac_f32_e32 v7, v124, v184
	v_fmac_f32_e32 v11, v125, v181
	v_fmac_f32_e32 v7, v125, v185
	v_fmac_f32_e32 v11, v126, v182
	v_fmac_f32_e32 v7, v126, v186
	v_fmac_f32_e32 v11, v127, v183
	v_fmac_f32_e32 v7, v127, v187
	v_fmac_f32_e32 v11, v128, v188
	v_fmac_f32_e32 v7, v128, v192
	v_fmac_f32_e32 v11, v129, v189
	v_fmac_f32_e32 v7, v129, v193
	v_fmac_f32_e32 v11, v130, v190
	v_fmac_f32_e32 v7, v130, v194
	v_fmac_f32_e32 v11, v131, v191
	v_fmac_f32_e32 v7, v131, v195
	v_mul_f32_e32 v6, v42, v11
	v_mul_f32_e32 v7, v42, v7
	s_and_saveexec_b64 s[22:23], s[10:11]
	s_xor_b64 s[22:23], exec, s[22:23]
	s_cbranch_execz .LBB0_1059
	ds_write_b32 v46, v6 offset:1020
	ds_write_b32 v45, v7 offset:1020
	s_andn2_saveexec_b64 s[22:23], s[22:23]
	s_cbranch_execnz .LBB0_1060
